# write-through (sc1) layer-0 bf16 output stores in both out-proj epilogues
# baseline (speedup 1.0000x reference)
;     ...
;         const char* base = lds + cb * BUF;
;         bf16x8 af[MT], bfr[NT];
; #pragma unroll
;         for (int nt = 0; nt < NT; ++nt) {
;             const int br = BM + (nt / NTS) * (BN / NSEG) + wc * (NTS * 16) + (nt % NTS) * 16;
;             bfr[nt] = *(const bf16x8*)(base + (br + l15) * 64 + rsw);
;         }
; #pragma unroll
;         for (int mt = 0; mt < MT; ++mt) af[mt] = *(const bf16x8*)(base + (wr * WM + mt * 16 + l15) * 64 + rsw);
;         constexpr int TOT = MT * NT, PER = (TOT + NIT - 1) / NIT;
; #pragma unroll
;         for (int part = 0; part < NIT; ++part) {
; #pragma unroll
;             for (int q = 0; q < PER; ++q) {
;                 const int idx = part * PER + q;
;                 if (idx < TOT) {
;                     const int mt = idx / NT, nt = idx % NT;
;                     acc[mt][nt] = SWAP ? mfma16(bfr[nt], af[mt], acc[mt][nt]) : mfma16(af[mt], bfr[nt], acc[mt][nt]);
;                 }
; DI void unit_O(const Params& p, char* lds, int l, int tile, int glu_tiles, int tile_b) {
;     ...
;     const int xrot = (int)(((blockIdx.x >> 3) + (blockIdx.x & 7) * 4) & 31) * 4;
;     const bf16_t* xbres = WS_PTR(const bf16_t, OFF_XB1) + ((size_t)((tile >> 1) * 32) * 128 + (tile & 1) * 64) * 32;
;     auto issue_x = [&](int half) {
;         if (l == 0) {
; #pragma unroll 1
;             for (int i = 0; i < 16; ++i) {
;                 const int pc = (wid * 16 + i + xrot) & 127, row = pc >> 2, phys = (pc & 3) * 64 + lane, logical = phys ^ (row & 15);
;                 __builtin_amdgcn_global_load_lds((const unsigned*)(xres + (r0 + half * 32 + row) * 1024 + logical * 4), (unsigned*)(XR + pc * 1024 + lane * 16), 16, 0, 0);
;             }
;         } else {
; #pragma unroll 1
;             for (int i = 0; i < 8; ++i) {
;                 const int pc = (wid * 8 + i + (xrot >> 1)) & 63, kt = pc >> 1, sub = pc & 1;
;                 __builtin_amdgcn_global_load_lds((const unsigned*)(xbres + ((size_t)kt * 128 + half * 32) * 32 + sub * 512 + lane * 8), (unsigned*)(XR + pc * 1024 + lane * 16), 16, 0, 0);
;             }
;         }
;     };
;     issue_x(0);
;     {
;         const float* gsrc = (tid < 256) ? (p.ln_g + l * 1024 + tid * 4) : (p.ln_b + l * 1024 + (tid - 256) * 4);
;         *(f32x4*)(GB + tid * 4) = *(const f32x4*)gsrc;
;     }
;     float* xo = (l == 0) ? WS_PTR(float, OFF_X1) : p.out;
;     bf16_t* xbo = WS_PTR(bf16_t, OFF_XB1);
.Lpo1_join:
.LBB0_100:
	s_waitcnt vmcnt(0)
	v_add_u32_e32 v0, 0x11000, v140
	s_barrier
	v_add_u32_e32 v134, v0, v141
	v_add_u32_e32 v0, v0, v139
	ds_read_b128 v[130:133], v134 offset:4096
	ds_read_b128 v[138:141], v0
	ds_read_b128 v[142:145], v134 offset:5120
	ds_read_b128 v[146:149], v0 offset:1024
	ds_read_b128 v[150:153], v134 offset:6144
	ds_read_b128 v[154:157], v134 offset:7168
	ds_read_b128 v[158:161], v134 offset:8192
	ds_read_b128 v[162:165], v134 offset:9216
	ds_read_b128 v[166:169], v134 offset:10240
	ds_read_b128 v[170:173], v134 offset:11264
	ds_read_b128 v[174:177], v0 offset:2048
	ds_read_b128 v[178:181], v0 offset:3072
	s_waitcnt lgkmcnt(0)
	v_mfma_f32_16x16x32_bf16 v[98:101], v[130:133], v[138:141], v[98:101]
	v_and_b32_e32 v197, 63, v136
	v_ashrrev_i32_e32 v236, 6, v136
	v_mfma_f32_16x16x32_bf16 v[94:97], v[142:145], v[138:141], v[94:97]
	v_mfma_f32_16x16x32_bf16 v[90:93], v[150:153], v[138:141], v[90:93]
	v_mfma_f32_16x16x32_bf16 v[86:89], v[154:157], v[138:141], v[86:89]
	v_mfma_f32_16x16x32_bf16 v[82:85], v[158:161], v[138:141], v[82:85]
	v_mfma_f32_16x16x32_bf16 v[78:81], v[162:165], v[138:141], v[78:81]
	v_mfma_f32_16x16x32_bf16 v[74:77], v[166:169], v[138:141], v[74:77]
	v_mfma_f32_16x16x32_bf16 v[70:73], v[170:173], v[138:141], v[70:73]
	v_mfma_f32_16x16x32_bf16 v[126:129], v[130:133], v[146:149], v[126:129]
	v_mfma_f32_16x16x32_bf16 v[122:125], v[142:145], v[146:149], v[122:125]
	v_mfma_f32_16x16x32_bf16 v[118:121], v[150:153], v[146:149], v[118:121]
	v_mfma_f32_16x16x32_bf16 v[114:117], v[154:157], v[146:149], v[114:117]
	v_mfma_f32_16x16x32_bf16 v[110:113], v[158:161], v[146:149], v[110:113]
	v_mfma_f32_16x16x32_bf16 v[106:109], v[162:165], v[146:149], v[106:109]
	v_mfma_f32_16x16x32_bf16 v[102:105], v[166:169], v[146:149], v[102:105]
	v_mfma_f32_16x16x32_bf16 v[66:69], v[170:173], v[146:149], v[66:69]
	v_mfma_f32_16x16x32_bf16 v[34:37], v[130:133], v[174:177], v[34:37]
	v_mfma_f32_16x16x32_bf16 v[30:33], v[142:145], v[174:177], v[30:33]
	v_mfma_f32_16x16x32_bf16 v[26:29], v[150:153], v[174:177], v[26:29]
	v_mfma_f32_16x16x32_bf16 v[22:25], v[154:157], v[174:177], v[22:25]
	v_mfma_f32_16x16x32_bf16 v[18:21], v[158:161], v[174:177], v[18:21]
	v_mfma_f32_16x16x32_bf16 v[14:17], v[162:165], v[174:177], v[14:17]
	v_mfma_f32_16x16x32_bf16 v[10:13], v[166:169], v[174:177], v[10:13]
	v_mfma_f32_16x16x32_bf16 v[6:9], v[170:173], v[174:177], v[6:9]
	v_mfma_f32_16x16x32_bf16 v[62:65], v[130:133], v[178:181], v[62:65]
	v_mfma_f32_16x16x32_bf16 v[58:61], v[142:145], v[178:181], v[58:61]
	v_mfma_f32_16x16x32_bf16 v[54:57], v[150:153], v[178:181], v[54:57]
	v_mfma_f32_16x16x32_bf16 v[50:53], v[154:157], v[178:181], v[50:53]
	v_mfma_f32_16x16x32_bf16 v[46:49], v[158:161], v[178:181], v[46:49]
	v_mfma_f32_16x16x32_bf16 v[42:45], v[162:165], v[178:181], v[42:45]
	v_mfma_f32_16x16x32_bf16 v[38:41], v[166:169], v[178:181], v[38:41]
	v_mfma_f32_16x16x32_bf16 v[2:5], v[170:173], v[178:181], v[2:5]
	s_barrier
	s_not_b64 s[6:7], s[10:11]
	v_and_b32_e32 v138, 15, v212
	v_bfe_u32 v139, v212, 4, 2
	v_lshrrev_b32_e32 v140, 6, v212
	v_and_b32_e32 v141, 63, v212
	v_readfirstlane_b32 s90, v140
	v_and_b32_e32 v142, 0xff, v212
	v_lshlrev_b32_e32 v142, 4, v142
	s_cmp_lt_u32 s90, 4
	s_cselect_b32 s92, s14, s12
	s_cselect_b32 s93, s15, s13
	s_nop 3
	global_load_dwordx4 v[176:179], v142, s[92:93]
	v_lshlrev_b32_e32 v143, 4, v212
	v_add_u32_e32 v143, 0x20000, v143
	v_lshlrev_b32_e32 v134, 6, v138
	v_add_u32_e32 v135, 0x22000, v134
	v_lshl_add_u32 v134, v140, 3, v135
	v_lshlrev_b32_e32 v136, 9, v140
	v_lshl_add_u32 v136, v139, 4, v136
	v_add_u32_e32 v136, 0x20000, v136
	s_cmp_lg_u64 s[10:11], 0
	s_cbranch_scc1 .Le1_l1
	s_lshl_b32 s40, s34, 18
	s_lshl_b32 s91, s90, 13
	s_add_u32 s96, s52, s40
	s_addc_u32 s97, s53, 0
	s_add_u32 s96, s96, s91
	s_addc_u32 s97, s97, 0
	s_lshl_b32 s40, s90, 1
	v_xor_b32_e32 v208, s40, v141
	v_lshlrev_b32_e32 v208, 4, v208
	s_add_u32 s40, s40, 1
	v_xor_b32_e32 v209, s40, v141
	v_lshlrev_b32_e32 v209, 4, v209
	v_lshlrev_b32_e32 v133, 12, v138
	v_lshl_add_u32 v133, v140, 9, v133
	v_add_u32_e32 v200, 0, v139
	v_xor_b32_e32 v200, v200, v138
	v_lshl_add_u32 v200, v200, 4, v133
	v_add_u32_e32 v204, 0x10000, v200
	v_add_u32_e32 v201, 4, v139
	v_xor_b32_e32 v201, v201, v138
	v_lshl_add_u32 v201, v201, 4, v133
	v_add_u32_e32 v205, 0x10000, v201
	v_add_u32_e32 v202, 8, v139
	v_xor_b32_e32 v202, v202, v138
	v_lshl_add_u32 v202, v202, 4, v133
	v_add_u32_e32 v206, 0x10000, v202
	v_add_u32_e32 v203, 12, v139
	v_xor_b32_e32 v203, v203, v138
	v_lshl_add_u32 v203, v203, 4, v133
	v_add_u32_e32 v207, 0x10000, v203
	v_and_b32_e32 v137, 1, v139
	v_lshlrev_b32_e32 v137, 5, v137
	v_lshrrev_b32_e32 v130, 1, v139
	v_lshl_or_b32 v137, v130, 4, v137
	v_lshl_or_b32 v137, v138, 6, v137
	v_lshl_or_b32 v137, v140, 15, v137
	s_lshr_b32 s40, s34, 1
	s_lshl_b32 s40, s40, 18
	s_and_b32 s46, s34, 1
	s_lshl_b32 s46, s46, 12
	s_add_u32 s40, s40, s46
	s_add_u32 s78, s56, s40
	s_addc_u32 s79, s57, 0
	s_add_u32 s92, s96, 0x0
	s_addc_u32 s93, s97, 0
	s_add_u32 s40, s91, 0x0
	s_mov_b32 m0, s40
	s_nop 0
	global_load_lds_dwordx4 v208, s[92:93]
	global_load_lds_dwordx4 v208, s[92:93] offset:1024
	global_load_lds_dwordx4 v208, s[92:93] offset:2048
	global_load_lds_dwordx4 v208, s[92:93] offset:3072
	s_add_u32 s92, s96, 0x1000
	s_addc_u32 s93, s97, 0
	s_add_u32 s40, s91, 0x1000
	s_mov_b32 m0, s40
	s_nop 0
	global_load_lds_dwordx4 v209, s[92:93]
	global_load_lds_dwordx4 v209, s[92:93] offset:1024
	global_load_lds_dwordx4 v209, s[92:93] offset:2048
	global_load_lds_dwordx4 v209, s[92:93] offset:3072
	s_add_u32 s92, s96, 0x10000
	s_addc_u32 s93, s97, 0
	s_add_u32 s40, s91, 0x10000
	s_mov_b32 m0, s40
	s_nop 0
	global_load_lds_dwordx4 v208, s[92:93]
	global_load_lds_dwordx4 v208, s[92:93] offset:1024
	global_load_lds_dwordx4 v208, s[92:93] offset:2048
	global_load_lds_dwordx4 v208, s[92:93] offset:3072
	s_add_u32 s92, s96, 0x11000
	s_addc_u32 s93, s97, 0
	s_add_u32 s40, s91, 0x11000
	s_mov_b32 m0, s40
	s_nop 0
	global_load_lds_dwordx4 v209, s[92:93]
	global_load_lds_dwordx4 v209, s[92:93] offset:1024
	global_load_lds_dwordx4 v209, s[92:93] offset:2048
	global_load_lds_dwordx4 v209, s[92:93] offset:3072
	s_waitcnt vmcnt(16)
	ds_write_b128 v143, v[176:179]
	s_waitcnt vmcnt(8) lgkmcnt(0)
	s_barrier
; DI float bf2f(unsigned b) { return __uint_as_float(b << 16); }
; DI void unit_O(const Params& p, char* lds, int l, int tile, int glu_tiles, int tile_b) {
;     ...
;         float s2[2], ss2[2];
; #pragma unroll
;         for (int mh = 0; mh < 2; ++mh) {
;             const int mt = half * 2 + mh, rl = mh * 16 + l15;
;             float s = 0.f, ss = 0.f;
; #pragma unroll
;             for (int nt = 0; nt < 8; ++nt) {
;                 f32x4 xr;
;                 if (l == 0) {
;                     const int chunk = wid * 32 + nt * 4 + quad;
;                     xr = *(const f32x4*)(XR + rl * 4096 + ((chunk ^ l15) << 4));
;                 } else {
;                     const u32x2 hb = *(const u32x2*)(XR + ((wid * 4 + (nt >> 1)) * 32 + rl) * 64 + (nt & 1) * 32 + quad * 8);
;                     xr = (f32x4){bf2f(hb[0] & 0xffffu), bf2f(hb[0] >> 16), bf2f(hb[1] & 0xffffu), bf2f(hb[1] >> 16)};
;                 }
; #pragma unroll
;                 for (int i = 0; i < 4; ++i) { const float v = acc[mt][nt][i] + DN_ALPHA * xr[i]; acc[mt][nt][i] = v; s += v; ss += v * v; }
;             }
;             s2[mh] = s; ss2[mh] = ss;
;         }
; #pragma unroll
;         for (int mh = 0; mh < 2; ++mh) { s2[mh] += __shfl_xor(s2[mh], 16); ss2[mh] += __shfl_xor(ss2[mh], 16); }
; #pragma unroll
;         for (int mh = 0; mh < 2; ++mh) { s2[mh] += __shfl_xor(s2[mh], 32); ss2[mh] += __shfl_xor(ss2[mh], 32); }
;         if (quad == 0) {
; #pragma unroll
;             for (int mh = 0; mh < 2; ++mh) *(f32x2*)&red[((mh * 16 + l15) * 8 + wid) * 2] = (f32x2){s2[mh], ss2[mh]};
;         }
;         __syncthreads();
;         if (half == 0) issue_x(1);
; #pragma unroll
;         for (int mh = 0; mh < 2; ++mh) {
;             const int mt = half * 2 + mh, rl = mh * 16 + l15, row = mt * 16 + l15;
;             float s = 0.f, ss = 0.f;
; #pragma unroll
;             for (int w = 0; w < 4; ++w) { const f32x4 v = *(const f32x4*)&red[rl * 16 + 4 * w]; s += v[0] + v[2]; ss += v[1] + v[3]; }
;             const float mu = s * (1.f / 1024.f);
;             const float var = ss * (1.f / 1024.f) - mu * mu;
;             const float rs = rsqrtf(var + LN_EPS);
	ds_read_b128 v[144:147], v200
	ds_read_b128 v[148:151], v201
	ds_read_b128 v[152:155], v202
	ds_read_b128 v[156:159], v203
	ds_read_b128 v[160:163], v200 offset:256
	ds_read_b128 v[164:167], v201 offset:256
	ds_read_b128 v[168:171], v202 offset:256
	ds_read_b128 v[172:175], v203 offset:256
	s_waitcnt lgkmcnt(7)
	v_fmac_f32_e32 v98, s58, v144
	v_fmac_f32_e32 v99, s58, v145
	v_fmac_f32_e32 v100, s58, v146
	v_fmac_f32_e32 v101, s58, v147
	v_mov_b32_e32 v196, v98
	v_mul_f32_e32 v197, v98, v98
	v_mov_b32_e32 v130, v99
	v_mul_f32_e32 v142, v99, v99
	v_add_f32_e32 v196, v196, v100
	v_fmac_f32_e32 v197, v100, v100
	v_add_f32_e32 v130, v130, v101
	v_fmac_f32_e32 v142, v101, v101
	s_waitcnt lgkmcnt(6)
	v_fmac_f32_e32 v94, s58, v148
	v_fmac_f32_e32 v95, s58, v149
	v_fmac_f32_e32 v96, s58, v150
	v_fmac_f32_e32 v97, s58, v151
	v_add_f32_e32 v196, v196, v94
	v_fmac_f32_e32 v197, v94, v94
	v_add_f32_e32 v130, v130, v95
	v_fmac_f32_e32 v142, v95, v95
	v_add_f32_e32 v196, v196, v96
	v_fmac_f32_e32 v197, v96, v96
	v_add_f32_e32 v130, v130, v97
	v_fmac_f32_e32 v142, v97, v97
	s_waitcnt lgkmcnt(5)
	v_fmac_f32_e32 v90, s58, v152
	v_fmac_f32_e32 v91, s58, v153
	v_fmac_f32_e32 v92, s58, v154
	v_fmac_f32_e32 v93, s58, v155
	v_add_f32_e32 v196, v196, v90
	v_fmac_f32_e32 v197, v90, v90
	v_add_f32_e32 v130, v130, v91
	v_fmac_f32_e32 v142, v91, v91
	v_add_f32_e32 v196, v196, v92
	v_fmac_f32_e32 v197, v92, v92
	v_add_f32_e32 v130, v130, v93
	v_fmac_f32_e32 v142, v93, v93
	s_waitcnt lgkmcnt(4)
	v_fmac_f32_e32 v86, s58, v156
	v_fmac_f32_e32 v87, s58, v157
	v_fmac_f32_e32 v88, s58, v158
	v_fmac_f32_e32 v89, s58, v159
	v_add_f32_e32 v196, v196, v86
	v_fmac_f32_e32 v197, v86, v86
	v_add_f32_e32 v130, v130, v87
	v_fmac_f32_e32 v142, v87, v87
	v_add_f32_e32 v196, v196, v88
	v_fmac_f32_e32 v197, v88, v88
	v_add_f32_e32 v130, v130, v89
	v_fmac_f32_e32 v142, v89, v89
	s_waitcnt lgkmcnt(3)
	v_fmac_f32_e32 v82, s58, v160
	v_fmac_f32_e32 v83, s58, v161
	v_fmac_f32_e32 v84, s58, v162
	v_fmac_f32_e32 v85, s58, v163
	v_add_f32_e32 v196, v196, v82
	v_fmac_f32_e32 v197, v82, v82
	v_add_f32_e32 v130, v130, v83
	v_fmac_f32_e32 v142, v83, v83
	v_add_f32_e32 v196, v196, v84
	v_fmac_f32_e32 v197, v84, v84
	v_add_f32_e32 v130, v130, v85
	v_fmac_f32_e32 v142, v85, v85
	s_waitcnt lgkmcnt(2)
	v_fmac_f32_e32 v78, s58, v164
	v_fmac_f32_e32 v79, s58, v165
	v_fmac_f32_e32 v80, s58, v166
	v_fmac_f32_e32 v81, s58, v167
	v_add_f32_e32 v196, v196, v78
	v_fmac_f32_e32 v197, v78, v78
	v_add_f32_e32 v130, v130, v79
	v_fmac_f32_e32 v142, v79, v79
	v_add_f32_e32 v196, v196, v80
	v_fmac_f32_e32 v197, v80, v80
	v_add_f32_e32 v130, v130, v81
	v_fmac_f32_e32 v142, v81, v81
	s_waitcnt lgkmcnt(1)
	v_fmac_f32_e32 v74, s58, v168
	v_fmac_f32_e32 v75, s58, v169
	v_fmac_f32_e32 v76, s58, v170
	v_fmac_f32_e32 v77, s58, v171
	v_add_f32_e32 v196, v196, v74
	v_fmac_f32_e32 v197, v74, v74
	v_add_f32_e32 v130, v130, v75
	v_fmac_f32_e32 v142, v75, v75
	v_add_f32_e32 v196, v196, v76
	v_fmac_f32_e32 v197, v76, v76
	v_add_f32_e32 v130, v130, v77
	v_fmac_f32_e32 v142, v77, v77
	s_waitcnt lgkmcnt(0)
	v_fmac_f32_e32 v70, s58, v172
	v_fmac_f32_e32 v71, s58, v173
	v_fmac_f32_e32 v72, s58, v174
	v_fmac_f32_e32 v73, s58, v175
	v_add_f32_e32 v196, v196, v70
	v_fmac_f32_e32 v197, v70, v70
	v_add_f32_e32 v130, v130, v71
	v_fmac_f32_e32 v142, v71, v71
	v_add_f32_e32 v196, v196, v72
	v_fmac_f32_e32 v197, v72, v72
	v_add_f32_e32 v130, v130, v73
	v_fmac_f32_e32 v142, v73, v73
	v_add_f32_e32 v196, v196, v130
	v_add_f32_e32 v197, v197, v142
	v_mov_b32_e32 v198, v196
	v_mov_b32_e32 v199, v197
	s_nop 1
	v_permlane16_swap_b32 v198, v196
	v_permlane16_swap_b32 v199, v197
	v_add_f32_e32 v196, v196, v198
	v_add_f32_e32 v197, v197, v199
	v_mov_b32_e32 v198, v196
	v_mov_b32_e32 v199, v197
	s_nop 1
	v_permlane32_swap_b32 v198, v196
	v_permlane32_swap_b32 v199, v197
	v_add_f32_e32 v196, v196, v198
	v_add_f32_e32 v197, v197, v199
	s_mov_b64 exec, 0xffff
	ds_write_b64 v134, v[196:197]
	s_mov_b64 exec, -1
	s_waitcnt lgkmcnt(0)
	s_barrier
	s_add_u32 s92, s96, 0x20000
	s_addc_u32 s93, s97, 0
	s_add_u32 s40, s91, 0x0
	s_mov_b32 m0, s40
	s_nop 0
	global_load_lds_dwordx4 v208, s[92:93]
	global_load_lds_dwordx4 v208, s[92:93] offset:1024
	global_load_lds_dwordx4 v208, s[92:93] offset:2048
	global_load_lds_dwordx4 v208, s[92:93] offset:3072
	s_add_u32 s92, s96, 0x21000
	s_addc_u32 s93, s97, 0
	s_add_u32 s40, s91, 0x1000
	s_mov_b32 m0, s40
	s_nop 0
	global_load_lds_dwordx4 v209, s[92:93]
	global_load_lds_dwordx4 v209, s[92:93] offset:1024
	global_load_lds_dwordx4 v209, s[92:93] offset:2048
	global_load_lds_dwordx4 v209, s[92:93] offset:3072
	ds_read_b128 v[160:163], v135 offset:0
	ds_read_b128 v[164:167], v135 offset:16
	ds_read_b128 v[168:171], v135 offset:32
	ds_read_b128 v[172:175], v135 offset:48
	s_waitcnt lgkmcnt(0)
	v_add_f32_e32 v160, v160, v162
	v_add_f32_e32 v161, v161, v163
	v_add_f32_e32 v164, v164, v166
	v_add_f32_e32 v165, v165, v167
	v_add_f32_e32 v168, v168, v170
	v_add_f32_e32 v169, v169, v171
	v_add_f32_e32 v172, v172, v174
	v_add_f32_e32 v173, v173, v175
	v_add_f32_e32 v160, v160, v164
	v_add_f32_e32 v161, v161, v165
	v_add_f32_e32 v168, v168, v172
	v_add_f32_e32 v169, v169, v173
	v_add_f32_e32 v160, v160, v168
	v_add_f32_e32 v161, v161, v169
	v_mul_f32_e32 v192, 0x3a800000, v160
	v_mul_f32_e32 v193, 0x3a800000, v161
	v_fma_f32 v193, -v192, v192, v193
	v_add_f32_e32 v193, 0x3727c5ac, v193
	v_rsq_f32_e32 v193, v193
	s_nop 0
	s_add_u32 s94, s78, 0x0
	s_addc_u32 s95, s79, 0
	ds_read_b128 v[176:179], v136
	ds_read_b128 v[180:183], v136 offset:4096
	ds_read_b128 v[184:187], v136 offset:64
	ds_read_b128 v[188:191], v136 offset:4160
	s_waitcnt lgkmcnt(2)
; DI unsigned pk2(float lo, float hi) { const f32x2 v = {lo, hi}; const bf16x2_t b = __builtin_convertvector(v, bf16x2_t); return __builtin_bit_cast(unsigned, b); }
; DI size_t xb_off(int tok, int col) { return ((size_t)(((tok >> 7) * 32 + (col >> 5)) * 128 + (tok & 127))) * 32 + (col & 31); }
; DI void unit_O(const Params& p, char* lds, int l, int tile, int glu_tiles, int tile_b) {
;     ...
;             float* orow = xo + (r0 + row) * 1024 + wid * 128 + quad * 4;
;             bf16_t* brow = xbo + xb_off((int)r0 + row, wid * 128) + quad * 4;
;             const float* gp = GB + wid * 128 + quad * 4;
; #pragma unroll
;             for (int nt = 0; nt < 8; ++nt) {
;                 const f32x4 g = *(const f32x4*)(gp + nt * 16), bb = *(const f32x4*)(gp + 1024 + nt * 16);
;                 f32x4 o;
; #pragma unroll
;                 for (int i = 0; i < 4; ++i) o[i] = (acc[mt][nt][i] - mu) * rs * g[i] + bb[i];
;                 if (l == 0) *(u32x2*)(brow + (nt >> 1) * 4096 + (nt & 1) * 16) = (u32x2){pk2(o[0], o[1]), pk2(o[2], o[3])};
;                 else *(f32x4*)(orow + nt * 16) = o;
;             }
	v_sub_f32_e32 v98, v98, v192
	v_mul_f32_e32 v98, v98, v193
	v_fma_f32 v98, v176, v98, v180
	v_sub_f32_e32 v99, v99, v192
	v_mul_f32_e32 v99, v99, v193
	v_fma_f32 v99, v177, v99, v181
	v_sub_f32_e32 v100, v100, v192
	v_mul_f32_e32 v100, v100, v193
	v_fma_f32 v100, v178, v100, v182
	v_sub_f32_e32 v101, v101, v192
	v_mul_f32_e32 v101, v101, v193
	v_fma_f32 v101, v179, v101, v183
	v_cvt_pk_bf16_f32 v144, v98, v99
	v_cvt_pk_bf16_f32 v145, v100, v101
	ds_read_b128 v[176:179], v136 offset:128
	ds_read_b128 v[180:183], v136 offset:4224
	s_waitcnt lgkmcnt(2)
	v_sub_f32_e32 v94, v94, v192
	v_mul_f32_e32 v94, v94, v193
	v_fma_f32 v94, v184, v94, v188
	v_sub_f32_e32 v95, v95, v192
	v_mul_f32_e32 v95, v95, v193
	v_fma_f32 v95, v185, v95, v189
	v_sub_f32_e32 v96, v96, v192
	v_mul_f32_e32 v96, v96, v193
	v_fma_f32 v96, v186, v96, v190
	v_sub_f32_e32 v97, v97, v192
	v_mul_f32_e32 v97, v97, v193
	v_fma_f32 v97, v187, v97, v191
	v_cvt_pk_bf16_f32 v146, v94, v95
	v_cvt_pk_bf16_f32 v147, v96, v97
	s_nop 1
	v_permlane16_swap_b32 v144, v146
	v_permlane16_swap_b32 v145, v147
	global_store_dwordx4 v137, v[144:147], s[94:95] sc1
	s_add_u32 s94, s94, 0x2000
	s_addc_u32 s95, s95, 0
	ds_read_b128 v[184:187], v136 offset:192
	ds_read_b128 v[188:191], v136 offset:4288
	s_waitcnt lgkmcnt(2)
	v_sub_f32_e32 v90, v90, v192
	v_mul_f32_e32 v90, v90, v193
	v_fma_f32 v90, v176, v90, v180
	v_sub_f32_e32 v91, v91, v192
	v_mul_f32_e32 v91, v91, v193
	v_fma_f32 v91, v177, v91, v181
	v_sub_f32_e32 v92, v92, v192
	v_mul_f32_e32 v92, v92, v193
	v_fma_f32 v92, v178, v92, v182
	v_sub_f32_e32 v93, v93, v192
	v_mul_f32_e32 v93, v93, v193
	v_fma_f32 v93, v179, v93, v183
	v_cvt_pk_bf16_f32 v152, v90, v91
	v_cvt_pk_bf16_f32 v153, v92, v93
	ds_read_b128 v[176:179], v136 offset:256
	ds_read_b128 v[180:183], v136 offset:4352
	s_waitcnt lgkmcnt(2)
	v_sub_f32_e32 v86, v86, v192
	v_mul_f32_e32 v86, v86, v193
	v_fma_f32 v86, v184, v86, v188
	v_sub_f32_e32 v87, v87, v192
	v_mul_f32_e32 v87, v87, v193
	v_fma_f32 v87, v185, v87, v189
	v_sub_f32_e32 v88, v88, v192
	v_mul_f32_e32 v88, v88, v193
	v_fma_f32 v88, v186, v88, v190
	v_sub_f32_e32 v89, v89, v192
	v_mul_f32_e32 v89, v89, v193
	v_fma_f32 v89, v187, v89, v191
	v_cvt_pk_bf16_f32 v154, v86, v87
	v_cvt_pk_bf16_f32 v155, v88, v89
	s_nop 1
	v_permlane16_swap_b32 v152, v154
	v_permlane16_swap_b32 v153, v155
	global_store_dwordx4 v137, v[152:155], s[94:95] sc1
	s_add_u32 s94, s94, 0x2000
	s_addc_u32 s95, s95, 0
	ds_read_b128 v[184:187], v136 offset:320
	ds_read_b128 v[188:191], v136 offset:4416
	s_waitcnt lgkmcnt(2)
	v_sub_f32_e32 v82, v82, v192
	v_mul_f32_e32 v82, v82, v193
	v_fma_f32 v82, v176, v82, v180
	v_sub_f32_e32 v83, v83, v192
	v_mul_f32_e32 v83, v83, v193
	v_fma_f32 v83, v177, v83, v181
	v_sub_f32_e32 v84, v84, v192
	v_mul_f32_e32 v84, v84, v193
	v_fma_f32 v84, v178, v84, v182
	v_sub_f32_e32 v85, v85, v192
	v_mul_f32_e32 v85, v85, v193
	v_fma_f32 v85, v179, v85, v183
	v_cvt_pk_bf16_f32 v144, v82, v83
	v_cvt_pk_bf16_f32 v145, v84, v85
	ds_read_b128 v[176:179], v136 offset:384
	ds_read_b128 v[180:183], v136 offset:4480
	s_waitcnt lgkmcnt(2)
	v_sub_f32_e32 v78, v78, v192
	v_mul_f32_e32 v78, v78, v193
	v_fma_f32 v78, v184, v78, v188
	v_sub_f32_e32 v79, v79, v192
	v_mul_f32_e32 v79, v79, v193
	v_fma_f32 v79, v185, v79, v189
	v_sub_f32_e32 v80, v80, v192
	v_mul_f32_e32 v80, v80, v193
	v_fma_f32 v80, v186, v80, v190
	v_sub_f32_e32 v81, v81, v192
	v_mul_f32_e32 v81, v81, v193
	v_fma_f32 v81, v187, v81, v191
	v_cvt_pk_bf16_f32 v146, v78, v79
	v_cvt_pk_bf16_f32 v147, v80, v81
	s_nop 1
	v_permlane16_swap_b32 v144, v146
	v_permlane16_swap_b32 v145, v147
	global_store_dwordx4 v137, v[144:147], s[94:95] sc1
	s_add_u32 s94, s94, 0x2000
	s_addc_u32 s95, s95, 0
	ds_read_b128 v[184:187], v136 offset:448
	ds_read_b128 v[188:191], v136 offset:4544
	s_waitcnt lgkmcnt(2)
	v_sub_f32_e32 v74, v74, v192
	v_mul_f32_e32 v74, v74, v193
	v_fma_f32 v74, v176, v74, v180
	v_sub_f32_e32 v75, v75, v192
	v_mul_f32_e32 v75, v75, v193
	v_fma_f32 v75, v177, v75, v181
	v_sub_f32_e32 v76, v76, v192
	v_mul_f32_e32 v76, v76, v193
	v_fma_f32 v76, v178, v76, v182
	v_sub_f32_e32 v77, v77, v192
	v_mul_f32_e32 v77, v77, v193
	v_fma_f32 v77, v179, v77, v183
	v_cvt_pk_bf16_f32 v152, v74, v75
	v_cvt_pk_bf16_f32 v153, v76, v77
	s_waitcnt lgkmcnt(0)
	v_sub_f32_e32 v70, v70, v192
	v_mul_f32_e32 v70, v70, v193
	v_fma_f32 v70, v184, v70, v188
	v_sub_f32_e32 v71, v71, v192
	v_mul_f32_e32 v71, v71, v193
	v_fma_f32 v71, v185, v71, v189
	v_sub_f32_e32 v72, v72, v192
	v_mul_f32_e32 v72, v72, v193
	v_fma_f32 v72, v186, v72, v190
	v_sub_f32_e32 v73, v73, v192
	v_mul_f32_e32 v73, v73, v193
	v_fma_f32 v73, v187, v73, v191
	v_cvt_pk_bf16_f32 v154, v70, v71
	v_cvt_pk_bf16_f32 v155, v72, v73
	s_nop 1
	v_permlane16_swap_b32 v152, v154
	v_permlane16_swap_b32 v153, v155
	global_store_dwordx4 v137, v[152:155], s[94:95] sc1
	s_waitcnt vmcnt(12) lgkmcnt(0)
	s_barrier
; DI float bf2f(unsigned b) { return __uint_as_float(b << 16); }
; DI void unit_O(const Params& p, char* lds, int l, int tile, int glu_tiles, int tile_b) {
;     ...
;         float s2[2], ss2[2];
; #pragma unroll
;         for (int mh = 0; mh < 2; ++mh) {
;             const int mt = half * 2 + mh, rl = mh * 16 + l15;
;             float s = 0.f, ss = 0.f;
; #pragma unroll
;             for (int nt = 0; nt < 8; ++nt) {
;                 f32x4 xr;
;                 if (l == 0) {
;                     const int chunk = wid * 32 + nt * 4 + quad;
;                     xr = *(const f32x4*)(XR + rl * 4096 + ((chunk ^ l15) << 4));
;                 } else {
;                     const u32x2 hb = *(const u32x2*)(XR + ((wid * 4 + (nt >> 1)) * 32 + rl) * 64 + (nt & 1) * 32 + quad * 8);
;                     xr = (f32x4){bf2f(hb[0] & 0xffffu), bf2f(hb[0] >> 16), bf2f(hb[1] & 0xffffu), bf2f(hb[1] >> 16)};
;                 }
; #pragma unroll
;                 for (int i = 0; i < 4; ++i) { const float v = acc[mt][nt][i] + DN_ALPHA * xr[i]; acc[mt][nt][i] = v; s += v; ss += v * v; }
;             }
;             s2[mh] = s; ss2[mh] = ss;
;         }
; #pragma unroll
;         for (int mh = 0; mh < 2; ++mh) { s2[mh] += __shfl_xor(s2[mh], 16); ss2[mh] += __shfl_xor(ss2[mh], 16); }
; #pragma unroll
;         for (int mh = 0; mh < 2; ++mh) { s2[mh] += __shfl_xor(s2[mh], 32); ss2[mh] += __shfl_xor(ss2[mh], 32); }
;         if (quad == 0) {
; #pragma unroll
;             for (int mh = 0; mh < 2; ++mh) *(f32x2*)&red[((mh * 16 + l15) * 8 + wid) * 2] = (f32x2){s2[mh], ss2[mh]};
;         }
;         __syncthreads();
;         if (half == 0) issue_x(1);
; #pragma unroll
;         for (int mh = 0; mh < 2; ++mh) {
;             const int mt = half * 2 + mh, rl = mh * 16 + l15, row = mt * 16 + l15;
;             float s = 0.f, ss = 0.f;
; #pragma unroll
;             for (int w = 0; w < 4; ++w) { const f32x4 v = *(const f32x4*)&red[rl * 16 + 4 * w]; s += v[0] + v[2]; ss += v[1] + v[3]; }
;             const float mu = s * (1.f / 1024.f);
;             const float var = ss * (1.f / 1024.f) - mu * mu;
;             const float rs = rsqrtf(var + LN_EPS);
	ds_read_b128 v[144:147], v204
	ds_read_b128 v[148:151], v205
	ds_read_b128 v[152:155], v206
	ds_read_b128 v[156:159], v207
	ds_read_b128 v[160:163], v204 offset:256
	ds_read_b128 v[164:167], v205 offset:256
	ds_read_b128 v[168:171], v206 offset:256
	ds_read_b128 v[172:175], v207 offset:256
	s_waitcnt lgkmcnt(7)
	v_fmac_f32_e32 v126, s58, v144
	v_fmac_f32_e32 v127, s58, v145
	v_fmac_f32_e32 v128, s58, v146
	v_fmac_f32_e32 v129, s58, v147
	v_mov_b32_e32 v196, v126
	v_mul_f32_e32 v197, v126, v126
	v_mov_b32_e32 v130, v127
	v_mul_f32_e32 v142, v127, v127
	v_add_f32_e32 v196, v196, v128
	v_fmac_f32_e32 v197, v128, v128
	v_add_f32_e32 v130, v130, v129
	v_fmac_f32_e32 v142, v129, v129
	s_waitcnt lgkmcnt(6)
	v_fmac_f32_e32 v122, s58, v148
	v_fmac_f32_e32 v123, s58, v149
	v_fmac_f32_e32 v124, s58, v150
	v_fmac_f32_e32 v125, s58, v151
	v_add_f32_e32 v196, v196, v122
	v_fmac_f32_e32 v197, v122, v122
	v_add_f32_e32 v130, v130, v123
	v_fmac_f32_e32 v142, v123, v123
	v_add_f32_e32 v196, v196, v124
	v_fmac_f32_e32 v197, v124, v124
	v_add_f32_e32 v130, v130, v125
	v_fmac_f32_e32 v142, v125, v125
	s_waitcnt lgkmcnt(5)
	v_fmac_f32_e32 v118, s58, v152
	v_fmac_f32_e32 v119, s58, v153
	v_fmac_f32_e32 v120, s58, v154
	v_fmac_f32_e32 v121, s58, v155
	v_add_f32_e32 v196, v196, v118
	v_fmac_f32_e32 v197, v118, v118
	v_add_f32_e32 v130, v130, v119
	v_fmac_f32_e32 v142, v119, v119
	v_add_f32_e32 v196, v196, v120
	v_fmac_f32_e32 v197, v120, v120
	v_add_f32_e32 v130, v130, v121
	v_fmac_f32_e32 v142, v121, v121
	s_waitcnt lgkmcnt(4)
	v_fmac_f32_e32 v114, s58, v156
	v_fmac_f32_e32 v115, s58, v157
	v_fmac_f32_e32 v116, s58, v158
	v_fmac_f32_e32 v117, s58, v159
	v_add_f32_e32 v196, v196, v114
	v_fmac_f32_e32 v197, v114, v114
	v_add_f32_e32 v130, v130, v115
	v_fmac_f32_e32 v142, v115, v115
	v_add_f32_e32 v196, v196, v116
	v_fmac_f32_e32 v197, v116, v116
	v_add_f32_e32 v130, v130, v117
	v_fmac_f32_e32 v142, v117, v117
	s_waitcnt lgkmcnt(3)
	v_fmac_f32_e32 v110, s58, v160
	v_fmac_f32_e32 v111, s58, v161
	v_fmac_f32_e32 v112, s58, v162
	v_fmac_f32_e32 v113, s58, v163
	v_add_f32_e32 v196, v196, v110
	v_fmac_f32_e32 v197, v110, v110
	v_add_f32_e32 v130, v130, v111
	v_fmac_f32_e32 v142, v111, v111
	v_add_f32_e32 v196, v196, v112
	v_fmac_f32_e32 v197, v112, v112
	v_add_f32_e32 v130, v130, v113
	v_fmac_f32_e32 v142, v113, v113
	s_waitcnt lgkmcnt(2)
	v_fmac_f32_e32 v106, s58, v164
	v_fmac_f32_e32 v107, s58, v165
	v_fmac_f32_e32 v108, s58, v166
	v_fmac_f32_e32 v109, s58, v167
	v_add_f32_e32 v196, v196, v106
	v_fmac_f32_e32 v197, v106, v106
	v_add_f32_e32 v130, v130, v107
	v_fmac_f32_e32 v142, v107, v107
	v_add_f32_e32 v196, v196, v108
	v_fmac_f32_e32 v197, v108, v108
	v_add_f32_e32 v130, v130, v109
	v_fmac_f32_e32 v142, v109, v109
	s_waitcnt lgkmcnt(1)
	v_fmac_f32_e32 v102, s58, v168
	v_fmac_f32_e32 v103, s58, v169
	v_fmac_f32_e32 v104, s58, v170
	v_fmac_f32_e32 v105, s58, v171
	v_add_f32_e32 v196, v196, v102
	v_fmac_f32_e32 v197, v102, v102
	v_add_f32_e32 v130, v130, v103
	v_fmac_f32_e32 v142, v103, v103
	v_add_f32_e32 v196, v196, v104
	v_fmac_f32_e32 v197, v104, v104
	v_add_f32_e32 v130, v130, v105
	v_fmac_f32_e32 v142, v105, v105
	s_waitcnt lgkmcnt(0)
	v_fmac_f32_e32 v66, s58, v172
	v_fmac_f32_e32 v67, s58, v173
	v_fmac_f32_e32 v68, s58, v174
	v_fmac_f32_e32 v69, s58, v175
	v_add_f32_e32 v196, v196, v66
	v_fmac_f32_e32 v197, v66, v66
	v_add_f32_e32 v130, v130, v67
	v_fmac_f32_e32 v142, v67, v67
	v_add_f32_e32 v196, v196, v68
	v_fmac_f32_e32 v197, v68, v68
	v_add_f32_e32 v130, v130, v69
	v_fmac_f32_e32 v142, v69, v69
	v_add_f32_e32 v196, v196, v130
	v_add_f32_e32 v197, v197, v142
	v_mov_b32_e32 v198, v196
	v_mov_b32_e32 v199, v197
	s_nop 1
	v_permlane16_swap_b32 v198, v196
	v_permlane16_swap_b32 v199, v197
	v_add_f32_e32 v196, v196, v198
	v_add_f32_e32 v197, v197, v199
	v_mov_b32_e32 v198, v196
	v_mov_b32_e32 v199, v197
	s_nop 1
	v_permlane32_swap_b32 v198, v196
	v_permlane32_swap_b32 v199, v197
	v_add_f32_e32 v196, v196, v198
	v_add_f32_e32 v197, v197, v199
	s_mov_b64 exec, 0xffff
	ds_write_b64 v134, v[196:197]
	s_mov_b64 exec, -1
	s_waitcnt lgkmcnt(0)
	s_barrier
	s_add_u32 s92, s96, 0x30000
	s_addc_u32 s93, s97, 0
	s_add_u32 s40, s91, 0x10000
	s_mov_b32 m0, s40
	s_nop 0
	global_load_lds_dwordx4 v208, s[92:93]
	global_load_lds_dwordx4 v208, s[92:93] offset:1024
	global_load_lds_dwordx4 v208, s[92:93] offset:2048
	global_load_lds_dwordx4 v208, s[92:93] offset:3072
	s_add_u32 s92, s96, 0x31000
	s_addc_u32 s93, s97, 0
	s_add_u32 s40, s91, 0x11000
	s_mov_b32 m0, s40
	s_nop 0
	global_load_lds_dwordx4 v209, s[92:93]
	global_load_lds_dwordx4 v209, s[92:93] offset:1024
	global_load_lds_dwordx4 v209, s[92:93] offset:2048
	global_load_lds_dwordx4 v209, s[92:93] offset:3072
	ds_read_b128 v[160:163], v135 offset:0
	ds_read_b128 v[164:167], v135 offset:16
	ds_read_b128 v[168:171], v135 offset:32
	ds_read_b128 v[172:175], v135 offset:48
	s_waitcnt lgkmcnt(0)
	v_add_f32_e32 v160, v160, v162
	v_add_f32_e32 v161, v161, v163
	v_add_f32_e32 v164, v164, v166
	v_add_f32_e32 v165, v165, v167
	v_add_f32_e32 v168, v168, v170
	v_add_f32_e32 v169, v169, v171
	v_add_f32_e32 v172, v172, v174
	v_add_f32_e32 v173, v173, v175
	v_add_f32_e32 v160, v160, v164
	v_add_f32_e32 v161, v161, v165
	v_add_f32_e32 v168, v168, v172
	v_add_f32_e32 v169, v169, v173
	v_add_f32_e32 v160, v160, v168
	v_add_f32_e32 v161, v161, v169
	v_mul_f32_e32 v192, 0x3a800000, v160
	v_mul_f32_e32 v193, 0x3a800000, v161
	v_fma_f32 v193, -v192, v192, v193
	v_add_f32_e32 v193, 0x3727c5ac, v193
	v_rsq_f32_e32 v193, v193
	s_nop 0
	s_add_u32 s94, s78, 0x400
	s_addc_u32 s95, s79, 0
	ds_read_b128 v[176:179], v136
	ds_read_b128 v[180:183], v136 offset:4096
	ds_read_b128 v[184:187], v136 offset:64
	ds_read_b128 v[188:191], v136 offset:4160
	s_waitcnt lgkmcnt(2)
; DI unsigned pk2(float lo, float hi) { const f32x2 v = {lo, hi}; const bf16x2_t b = __builtin_convertvector(v, bf16x2_t); return __builtin_bit_cast(unsigned, b); }
; DI size_t xb_off(int tok, int col) { return ((size_t)(((tok >> 7) * 32 + (col >> 5)) * 128 + (tok & 127))) * 32 + (col & 31); }
; DI void unit_O(const Params& p, char* lds, int l, int tile, int glu_tiles, int tile_b) {
;     ...
;             float* orow = xo + (r0 + row) * 1024 + wid * 128 + quad * 4;
;             bf16_t* brow = xbo + xb_off((int)r0 + row, wid * 128) + quad * 4;
;             const float* gp = GB + wid * 128 + quad * 4;
; #pragma unroll
;             for (int nt = 0; nt < 8; ++nt) {
;                 const f32x4 g = *(const f32x4*)(gp + nt * 16), bb = *(const f32x4*)(gp + 1024 + nt * 16);
;                 f32x4 o;
; #pragma unroll
;                 for (int i = 0; i < 4; ++i) o[i] = (acc[mt][nt][i] - mu) * rs * g[i] + bb[i];
;                 if (l == 0) *(u32x2*)(brow + (nt >> 1) * 4096 + (nt & 1) * 16) = (u32x2){pk2(o[0], o[1]), pk2(o[2], o[3])};
;                 else *(f32x4*)(orow + nt * 16) = o;
;             }
	v_sub_f32_e32 v126, v126, v192
	v_mul_f32_e32 v126, v126, v193
	v_fma_f32 v126, v176, v126, v180
	v_sub_f32_e32 v127, v127, v192
	v_mul_f32_e32 v127, v127, v193
	v_fma_f32 v127, v177, v127, v181
	v_sub_f32_e32 v128, v128, v192
	v_mul_f32_e32 v128, v128, v193
	v_fma_f32 v128, v178, v128, v182
	v_sub_f32_e32 v129, v129, v192
	v_mul_f32_e32 v129, v129, v193
	v_fma_f32 v129, v179, v129, v183
	v_cvt_pk_bf16_f32 v144, v126, v127
	v_cvt_pk_bf16_f32 v145, v128, v129
	ds_read_b128 v[176:179], v136 offset:128
	ds_read_b128 v[180:183], v136 offset:4224
	s_waitcnt lgkmcnt(2)
	v_sub_f32_e32 v122, v122, v192
	v_mul_f32_e32 v122, v122, v193
	v_fma_f32 v122, v184, v122, v188
	v_sub_f32_e32 v123, v123, v192
	v_mul_f32_e32 v123, v123, v193
	v_fma_f32 v123, v185, v123, v189
	v_sub_f32_e32 v124, v124, v192
	v_mul_f32_e32 v124, v124, v193
	v_fma_f32 v124, v186, v124, v190
	v_sub_f32_e32 v125, v125, v192
	v_mul_f32_e32 v125, v125, v193
	v_fma_f32 v125, v187, v125, v191
	v_cvt_pk_bf16_f32 v146, v122, v123
	v_cvt_pk_bf16_f32 v147, v124, v125
	s_nop 1
	v_permlane16_swap_b32 v144, v146
	v_permlane16_swap_b32 v145, v147
	global_store_dwordx4 v137, v[144:147], s[94:95] sc1
	s_add_u32 s94, s94, 0x2000
	s_addc_u32 s95, s95, 0
	ds_read_b128 v[184:187], v136 offset:192
	ds_read_b128 v[188:191], v136 offset:4288
	s_waitcnt lgkmcnt(2)
	v_sub_f32_e32 v118, v118, v192
	v_mul_f32_e32 v118, v118, v193
	v_fma_f32 v118, v176, v118, v180
	v_sub_f32_e32 v119, v119, v192
	v_mul_f32_e32 v119, v119, v193
	v_fma_f32 v119, v177, v119, v181
	v_sub_f32_e32 v120, v120, v192
	v_mul_f32_e32 v120, v120, v193
	v_fma_f32 v120, v178, v120, v182
	v_sub_f32_e32 v121, v121, v192
	v_mul_f32_e32 v121, v121, v193
	v_fma_f32 v121, v179, v121, v183
	v_cvt_pk_bf16_f32 v152, v118, v119
	v_cvt_pk_bf16_f32 v153, v120, v121
	ds_read_b128 v[176:179], v136 offset:256
	ds_read_b128 v[180:183], v136 offset:4352
	s_waitcnt lgkmcnt(2)
	v_sub_f32_e32 v114, v114, v192
	v_mul_f32_e32 v114, v114, v193
	v_fma_f32 v114, v184, v114, v188
	v_sub_f32_e32 v115, v115, v192
	v_mul_f32_e32 v115, v115, v193
	v_fma_f32 v115, v185, v115, v189
	v_sub_f32_e32 v116, v116, v192
	v_mul_f32_e32 v116, v116, v193
	v_fma_f32 v116, v186, v116, v190
	v_sub_f32_e32 v117, v117, v192
	v_mul_f32_e32 v117, v117, v193
	v_fma_f32 v117, v187, v117, v191
	v_cvt_pk_bf16_f32 v154, v114, v115
	v_cvt_pk_bf16_f32 v155, v116, v117
	s_nop 1
	v_permlane16_swap_b32 v152, v154
	v_permlane16_swap_b32 v153, v155
	global_store_dwordx4 v137, v[152:155], s[94:95] sc1
	s_add_u32 s94, s94, 0x2000
	s_addc_u32 s95, s95, 0
	ds_read_b128 v[184:187], v136 offset:320
	ds_read_b128 v[188:191], v136 offset:4416
	s_waitcnt lgkmcnt(2)
	v_sub_f32_e32 v110, v110, v192
	v_mul_f32_e32 v110, v110, v193
	v_fma_f32 v110, v176, v110, v180
	v_sub_f32_e32 v111, v111, v192
	v_mul_f32_e32 v111, v111, v193
	v_fma_f32 v111, v177, v111, v181
	v_sub_f32_e32 v112, v112, v192
	v_mul_f32_e32 v112, v112, v193
	v_fma_f32 v112, v178, v112, v182
	v_sub_f32_e32 v113, v113, v192
	v_mul_f32_e32 v113, v113, v193
	v_fma_f32 v113, v179, v113, v183
	v_cvt_pk_bf16_f32 v144, v110, v111
	v_cvt_pk_bf16_f32 v145, v112, v113
	ds_read_b128 v[176:179], v136 offset:384
	ds_read_b128 v[180:183], v136 offset:4480
	s_waitcnt lgkmcnt(2)
	v_sub_f32_e32 v106, v106, v192
	v_mul_f32_e32 v106, v106, v193
	v_fma_f32 v106, v184, v106, v188
	v_sub_f32_e32 v107, v107, v192
	v_mul_f32_e32 v107, v107, v193
	v_fma_f32 v107, v185, v107, v189
	v_sub_f32_e32 v108, v108, v192
	v_mul_f32_e32 v108, v108, v193
	v_fma_f32 v108, v186, v108, v190
	v_sub_f32_e32 v109, v109, v192
	v_mul_f32_e32 v109, v109, v193
	v_fma_f32 v109, v187, v109, v191
	v_cvt_pk_bf16_f32 v146, v106, v107
	v_cvt_pk_bf16_f32 v147, v108, v109
	s_nop 1
	v_permlane16_swap_b32 v144, v146
	v_permlane16_swap_b32 v145, v147
	global_store_dwordx4 v137, v[144:147], s[94:95] sc1
	s_add_u32 s94, s94, 0x2000
	s_addc_u32 s95, s95, 0
	ds_read_b128 v[184:187], v136 offset:448
	ds_read_b128 v[188:191], v136 offset:4544
	s_waitcnt lgkmcnt(2)
	v_sub_f32_e32 v102, v102, v192
	v_mul_f32_e32 v102, v102, v193
	v_fma_f32 v102, v176, v102, v180
	v_sub_f32_e32 v103, v103, v192
	v_mul_f32_e32 v103, v103, v193
	v_fma_f32 v103, v177, v103, v181
	v_sub_f32_e32 v104, v104, v192
	v_mul_f32_e32 v104, v104, v193
	v_fma_f32 v104, v178, v104, v182
	v_sub_f32_e32 v105, v105, v192
	v_mul_f32_e32 v105, v105, v193
	v_fma_f32 v105, v179, v105, v183
	v_cvt_pk_bf16_f32 v152, v102, v103
	v_cvt_pk_bf16_f32 v153, v104, v105
	s_waitcnt lgkmcnt(0)
	v_sub_f32_e32 v66, v66, v192
	v_mul_f32_e32 v66, v66, v193
	v_fma_f32 v66, v184, v66, v188
	v_sub_f32_e32 v67, v67, v192
	v_mul_f32_e32 v67, v67, v193
	v_fma_f32 v67, v185, v67, v189
	v_sub_f32_e32 v68, v68, v192
	v_mul_f32_e32 v68, v68, v193
	v_fma_f32 v68, v186, v68, v190
	v_sub_f32_e32 v69, v69, v192
	v_mul_f32_e32 v69, v69, v193
	v_fma_f32 v69, v187, v69, v191
	v_cvt_pk_bf16_f32 v154, v66, v67
	v_cvt_pk_bf16_f32 v155, v68, v69
	s_nop 1
	v_permlane16_swap_b32 v152, v154
	v_permlane16_swap_b32 v153, v155
	global_store_dwordx4 v137, v[152:155], s[94:95] sc1
	s_waitcnt vmcnt(16) lgkmcnt(0)
	s_barrier
; DI void unit_O(const Params& p, char* lds, int l, int tile, int glu_tiles, int tile_b) {
;     ...
;         float s2[2], ss2[2];
; #pragma unroll
;         for (int mh = 0; mh < 2; ++mh) {
;             const int mt = half * 2 + mh, rl = mh * 16 + l15;
;             float s = 0.f, ss = 0.f;
; #pragma unroll
;             for (int nt = 0; nt < 8; ++nt) {
;                 f32x4 xr;
;                 if (l == 0) {
;                     const int chunk = wid * 32 + nt * 4 + quad;
;                     xr = *(const f32x4*)(XR + rl * 4096 + ((chunk ^ l15) << 4));
;                 } else {
;                     const u32x2 hb = *(const u32x2*)(XR + ((wid * 4 + (nt >> 1)) * 32 + rl) * 64 + (nt & 1) * 32 + quad * 8);
;                     xr = (f32x4){bf2f(hb[0] & 0xffffu), bf2f(hb[0] >> 16), bf2f(hb[1] & 0xffffu), bf2f(hb[1] >> 16)};
;                 }
; #pragma unroll
;                 for (int i = 0; i < 4; ++i) { const float v = acc[mt][nt][i] + DN_ALPHA * xr[i]; acc[mt][nt][i] = v; s += v; ss += v * v; }
;             }
;             s2[mh] = s; ss2[mh] = ss;
;         }
; #pragma unroll
;         for (int mh = 0; mh < 2; ++mh) { s2[mh] += __shfl_xor(s2[mh], 16); ss2[mh] += __shfl_xor(ss2[mh], 16); }
; #pragma unroll
;         for (int mh = 0; mh < 2; ++mh) { s2[mh] += __shfl_xor(s2[mh], 32); ss2[mh] += __shfl_xor(ss2[mh], 32); }
;         if (quad == 0) {
; #pragma unroll
;             for (int mh = 0; mh < 2; ++mh) *(f32x2*)&red[((mh * 16 + l15) * 8 + wid) * 2] = (f32x2){s2[mh], ss2[mh]};
;         }
;         __syncthreads();
;         if (half == 0) issue_x(1);
; #pragma unroll
;         for (int mh = 0; mh < 2; ++mh) {
;             const int mt = half * 2 + mh, rl = mh * 16 + l15, row = mt * 16 + l15;
;             float s = 0.f, ss = 0.f;
; #pragma unroll
;             for (int w = 0; w < 4; ++w) { const f32x4 v = *(const f32x4*)&red[rl * 16 + 4 * w]; s += v[0] + v[2]; ss += v[1] + v[3]; }
;             const float mu = s * (1.f / 1024.f);
;             const float var = ss * (1.f / 1024.f) - mu * mu;
;             const float rs = rsqrtf(var + LN_EPS);
;             float* orow = xo + (r0 + row) * 1024 + wid * 128 + quad * 4;
;             bf16_t* brow = xbo + xb_off((int)r0 + row, wid * 128) + quad * 4;
;             const float* gp = GB + wid * 128 + quad * 4;
; #pragma unroll
;             for (int nt = 0; nt < 8; ++nt) {
	ds_read_b128 v[144:147], v200
	ds_read_b128 v[148:151], v201
	ds_read_b128 v[152:155], v202
	ds_read_b128 v[156:159], v203
	ds_read_b128 v[160:163], v200 offset:256
	ds_read_b128 v[164:167], v201 offset:256
	ds_read_b128 v[168:171], v202 offset:256
	ds_read_b128 v[172:175], v203 offset:256
	s_waitcnt lgkmcnt(7)
	v_fmac_f32_e32 v34, s58, v144
	v_fmac_f32_e32 v35, s58, v145
	v_fmac_f32_e32 v36, s58, v146
	v_fmac_f32_e32 v37, s58, v147
	v_mov_b32_e32 v196, v34
	v_mul_f32_e32 v197, v34, v34
	v_mov_b32_e32 v130, v35
	v_mul_f32_e32 v142, v35, v35
	v_add_f32_e32 v196, v196, v36
	v_fmac_f32_e32 v197, v36, v36
	v_add_f32_e32 v130, v130, v37
	v_fmac_f32_e32 v142, v37, v37
	s_waitcnt lgkmcnt(6)
	v_fmac_f32_e32 v30, s58, v148
	v_fmac_f32_e32 v31, s58, v149
	v_fmac_f32_e32 v32, s58, v150
	v_fmac_f32_e32 v33, s58, v151
	v_add_f32_e32 v196, v196, v30
	v_fmac_f32_e32 v197, v30, v30
	v_add_f32_e32 v130, v130, v31
	v_fmac_f32_e32 v142, v31, v31
	v_add_f32_e32 v196, v196, v32
	v_fmac_f32_e32 v197, v32, v32
	v_add_f32_e32 v130, v130, v33
	v_fmac_f32_e32 v142, v33, v33
	s_waitcnt lgkmcnt(5)
	v_fmac_f32_e32 v26, s58, v152
	v_fmac_f32_e32 v27, s58, v153
	v_fmac_f32_e32 v28, s58, v154
	v_fmac_f32_e32 v29, s58, v155
	v_add_f32_e32 v196, v196, v26
	v_fmac_f32_e32 v197, v26, v26
	v_add_f32_e32 v130, v130, v27
	v_fmac_f32_e32 v142, v27, v27
	v_add_f32_e32 v196, v196, v28
	v_fmac_f32_e32 v197, v28, v28
	v_add_f32_e32 v130, v130, v29
	v_fmac_f32_e32 v142, v29, v29
	s_waitcnt lgkmcnt(4)
	v_fmac_f32_e32 v22, s58, v156
	v_fmac_f32_e32 v23, s58, v157
	v_fmac_f32_e32 v24, s58, v158
	v_fmac_f32_e32 v25, s58, v159
	v_add_f32_e32 v196, v196, v22
	v_fmac_f32_e32 v197, v22, v22
	v_add_f32_e32 v130, v130, v23
	v_fmac_f32_e32 v142, v23, v23
	v_add_f32_e32 v196, v196, v24
	v_fmac_f32_e32 v197, v24, v24
	v_add_f32_e32 v130, v130, v25
	v_fmac_f32_e32 v142, v25, v25
	s_waitcnt lgkmcnt(3)
	v_fmac_f32_e32 v18, s58, v160
	v_fmac_f32_e32 v19, s58, v161
	v_fmac_f32_e32 v20, s58, v162
	v_fmac_f32_e32 v21, s58, v163
	v_add_f32_e32 v196, v196, v18
	v_fmac_f32_e32 v197, v18, v18
	v_add_f32_e32 v130, v130, v19
	v_fmac_f32_e32 v142, v19, v19
	v_add_f32_e32 v196, v196, v20
	v_fmac_f32_e32 v197, v20, v20
	v_add_f32_e32 v130, v130, v21
	v_fmac_f32_e32 v142, v21, v21
	s_waitcnt lgkmcnt(2)
	v_fmac_f32_e32 v14, s58, v164
	v_fmac_f32_e32 v15, s58, v165
	v_fmac_f32_e32 v16, s58, v166
	v_fmac_f32_e32 v17, s58, v167
	v_add_f32_e32 v196, v196, v14
	v_fmac_f32_e32 v197, v14, v14
	v_add_f32_e32 v130, v130, v15
	v_fmac_f32_e32 v142, v15, v15
	v_add_f32_e32 v196, v196, v16
	v_fmac_f32_e32 v197, v16, v16
	v_add_f32_e32 v130, v130, v17
	v_fmac_f32_e32 v142, v17, v17
	s_waitcnt lgkmcnt(1)
	v_fmac_f32_e32 v10, s58, v168
	v_fmac_f32_e32 v11, s58, v169
	v_fmac_f32_e32 v12, s58, v170
	v_fmac_f32_e32 v13, s58, v171
	v_add_f32_e32 v196, v196, v10
	v_fmac_f32_e32 v197, v10, v10
	v_add_f32_e32 v130, v130, v11
	v_fmac_f32_e32 v142, v11, v11
	v_add_f32_e32 v196, v196, v12
	v_fmac_f32_e32 v197, v12, v12
	v_add_f32_e32 v130, v130, v13
	v_fmac_f32_e32 v142, v13, v13
	s_waitcnt lgkmcnt(0)
	v_fmac_f32_e32 v6, s58, v172
	v_fmac_f32_e32 v7, s58, v173
	v_fmac_f32_e32 v8, s58, v174
	v_fmac_f32_e32 v9, s58, v175
	v_add_f32_e32 v196, v196, v6
	v_fmac_f32_e32 v197, v6, v6
	v_add_f32_e32 v130, v130, v7
	v_fmac_f32_e32 v142, v7, v7
	v_add_f32_e32 v196, v196, v8
	v_fmac_f32_e32 v197, v8, v8
	v_add_f32_e32 v130, v130, v9
	v_fmac_f32_e32 v142, v9, v9
	v_add_f32_e32 v196, v196, v130
	v_add_f32_e32 v197, v197, v142
	v_mov_b32_e32 v198, v196
	v_mov_b32_e32 v199, v197
	s_nop 1
	v_permlane16_swap_b32 v198, v196
	v_permlane16_swap_b32 v199, v197
	v_add_f32_e32 v196, v196, v198
	v_add_f32_e32 v197, v197, v199
	v_mov_b32_e32 v198, v196
	v_mov_b32_e32 v199, v197
	s_nop 1
	v_permlane32_swap_b32 v198, v196
	v_permlane32_swap_b32 v199, v197
	v_add_f32_e32 v196, v196, v198
	v_add_f32_e32 v197, v197, v199
	s_mov_b64 exec, 0xffff
	ds_write_b64 v134, v[196:197]
	s_mov_b64 exec, -1
	s_waitcnt lgkmcnt(0)
	s_barrier
	ds_read_b128 v[160:163], v135 offset:0
	ds_read_b128 v[164:167], v135 offset:16
	ds_read_b128 v[168:171], v135 offset:32
	ds_read_b128 v[172:175], v135 offset:48
	s_waitcnt lgkmcnt(0)
	v_add_f32_e32 v160, v160, v162
	v_add_f32_e32 v161, v161, v163
	v_add_f32_e32 v164, v164, v166
	v_add_f32_e32 v165, v165, v167
	v_add_f32_e32 v168, v168, v170
	v_add_f32_e32 v169, v169, v171
	v_add_f32_e32 v172, v172, v174
	v_add_f32_e32 v173, v173, v175
	v_add_f32_e32 v160, v160, v164
	v_add_f32_e32 v161, v161, v165
	v_add_f32_e32 v168, v168, v172
	v_add_f32_e32 v169, v169, v173
	v_add_f32_e32 v160, v160, v168
	v_add_f32_e32 v161, v161, v169
	v_mul_f32_e32 v192, 0x3a800000, v160
	v_mul_f32_e32 v193, 0x3a800000, v161
	v_fma_f32 v193, -v192, v192, v193
	v_add_f32_e32 v193, 0x3727c5ac, v193
	v_rsq_f32_e32 v193, v193
	s_nop 0
	s_add_u32 s94, s78, 0x800
	s_addc_u32 s95, s79, 0
	ds_read_b128 v[176:179], v136
	ds_read_b128 v[180:183], v136 offset:4096
	ds_read_b128 v[184:187], v136 offset:64
	ds_read_b128 v[188:191], v136 offset:4160
	s_waitcnt lgkmcnt(2)
	v_sub_f32_e32 v34, v34, v192
	v_mul_f32_e32 v34, v34, v193
	v_fma_f32 v34, v176, v34, v180
	v_sub_f32_e32 v35, v35, v192
	v_mul_f32_e32 v35, v35, v193
	v_fma_f32 v35, v177, v35, v181
	v_sub_f32_e32 v36, v36, v192
	v_mul_f32_e32 v36, v36, v193
	v_fma_f32 v36, v178, v36, v182
	v_sub_f32_e32 v37, v37, v192
	v_mul_f32_e32 v37, v37, v193
	v_fma_f32 v37, v179, v37, v183
	v_cvt_pk_bf16_f32 v144, v34, v35
	v_cvt_pk_bf16_f32 v145, v36, v37
	ds_read_b128 v[176:179], v136 offset:128
	ds_read_b128 v[180:183], v136 offset:4224
	s_waitcnt lgkmcnt(2)
; DI unsigned pk2(float lo, float hi) { const f32x2 v = {lo, hi}; const bf16x2_t b = __builtin_convertvector(v, bf16x2_t); return __builtin_bit_cast(unsigned, b); }
; DI void unit_O(const Params& p, char* lds, int l, int tile, int glu_tiles, int tile_b) {
;     ...
; #pragma unroll
;             for (int nt = 0; nt < 8; ++nt) {
;                 const f32x4 g = *(const f32x4*)(gp + nt * 16), bb = *(const f32x4*)(gp + 1024 + nt * 16);
;                 f32x4 o;
; #pragma unroll
;                 for (int i = 0; i < 4; ++i) o[i] = (acc[mt][nt][i] - mu) * rs * g[i] + bb[i];
;                 if (l == 0) *(u32x2*)(brow + (nt >> 1) * 4096 + (nt & 1) * 16) = (u32x2){pk2(o[0], o[1]), pk2(o[2], o[3])};
;                 else *(f32x4*)(orow + nt * 16) = o;
;             }
	v_sub_f32_e32 v30, v30, v192
	v_mul_f32_e32 v30, v30, v193
	v_fma_f32 v30, v184, v30, v188
	v_sub_f32_e32 v31, v31, v192
	v_mul_f32_e32 v31, v31, v193
	v_fma_f32 v31, v185, v31, v189
	v_sub_f32_e32 v32, v32, v192
	v_mul_f32_e32 v32, v32, v193
	v_fma_f32 v32, v186, v32, v190
	v_sub_f32_e32 v33, v33, v192
	v_mul_f32_e32 v33, v33, v193
	v_fma_f32 v33, v187, v33, v191
	v_cvt_pk_bf16_f32 v146, v30, v31
	v_cvt_pk_bf16_f32 v147, v32, v33
	s_nop 1
	v_permlane16_swap_b32 v144, v146
	v_permlane16_swap_b32 v145, v147
	global_store_dwordx4 v137, v[144:147], s[94:95] sc1
	s_add_u32 s94, s94, 0x2000
	s_addc_u32 s95, s95, 0
	ds_read_b128 v[184:187], v136 offset:192
	ds_read_b128 v[188:191], v136 offset:4288
	s_waitcnt lgkmcnt(2)
	v_sub_f32_e32 v26, v26, v192
	v_mul_f32_e32 v26, v26, v193
	v_fma_f32 v26, v176, v26, v180
	v_sub_f32_e32 v27, v27, v192
	v_mul_f32_e32 v27, v27, v193
	v_fma_f32 v27, v177, v27, v181
	v_sub_f32_e32 v28, v28, v192
	v_mul_f32_e32 v28, v28, v193
	v_fma_f32 v28, v178, v28, v182
	v_sub_f32_e32 v29, v29, v192
	v_mul_f32_e32 v29, v29, v193
	v_fma_f32 v29, v179, v29, v183
	v_cvt_pk_bf16_f32 v152, v26, v27
	v_cvt_pk_bf16_f32 v153, v28, v29
	ds_read_b128 v[176:179], v136 offset:256
	ds_read_b128 v[180:183], v136 offset:4352
	s_waitcnt lgkmcnt(2)
	v_sub_f32_e32 v22, v22, v192
	v_mul_f32_e32 v22, v22, v193
	v_fma_f32 v22, v184, v22, v188
	v_sub_f32_e32 v23, v23, v192
	v_mul_f32_e32 v23, v23, v193
	v_fma_f32 v23, v185, v23, v189
	v_sub_f32_e32 v24, v24, v192
	v_mul_f32_e32 v24, v24, v193
	v_fma_f32 v24, v186, v24, v190
	v_sub_f32_e32 v25, v25, v192
	v_mul_f32_e32 v25, v25, v193
	v_fma_f32 v25, v187, v25, v191
	v_cvt_pk_bf16_f32 v154, v22, v23
	v_cvt_pk_bf16_f32 v155, v24, v25
	s_nop 1
	v_permlane16_swap_b32 v152, v154
	v_permlane16_swap_b32 v153, v155
	global_store_dwordx4 v137, v[152:155], s[94:95] sc1
	s_add_u32 s94, s94, 0x2000
	s_addc_u32 s95, s95, 0
	ds_read_b128 v[184:187], v136 offset:320
	ds_read_b128 v[188:191], v136 offset:4416
	s_waitcnt lgkmcnt(2)
	v_sub_f32_e32 v18, v18, v192
	v_mul_f32_e32 v18, v18, v193
	v_fma_f32 v18, v176, v18, v180
	v_sub_f32_e32 v19, v19, v192
	v_mul_f32_e32 v19, v19, v193
	v_fma_f32 v19, v177, v19, v181
	v_sub_f32_e32 v20, v20, v192
	v_mul_f32_e32 v20, v20, v193
	v_fma_f32 v20, v178, v20, v182
	v_sub_f32_e32 v21, v21, v192
	v_mul_f32_e32 v21, v21, v193
	v_fma_f32 v21, v179, v21, v183
	v_cvt_pk_bf16_f32 v144, v18, v19
	v_cvt_pk_bf16_f32 v145, v20, v21
	ds_read_b128 v[176:179], v136 offset:384
	ds_read_b128 v[180:183], v136 offset:4480
	s_waitcnt lgkmcnt(2)
	v_sub_f32_e32 v14, v14, v192
	v_mul_f32_e32 v14, v14, v193
	v_fma_f32 v14, v184, v14, v188
	v_sub_f32_e32 v15, v15, v192
	v_mul_f32_e32 v15, v15, v193
	v_fma_f32 v15, v185, v15, v189
	v_sub_f32_e32 v16, v16, v192
	v_mul_f32_e32 v16, v16, v193
	v_fma_f32 v16, v186, v16, v190
	v_sub_f32_e32 v17, v17, v192
	v_mul_f32_e32 v17, v17, v193
	v_fma_f32 v17, v187, v17, v191
	v_cvt_pk_bf16_f32 v146, v14, v15
	v_cvt_pk_bf16_f32 v147, v16, v17
	s_nop 1
	v_permlane16_swap_b32 v144, v146
	v_permlane16_swap_b32 v145, v147
	global_store_dwordx4 v137, v[144:147], s[94:95] sc1
	s_add_u32 s94, s94, 0x2000
	s_addc_u32 s95, s95, 0
	ds_read_b128 v[184:187], v136 offset:448
	ds_read_b128 v[188:191], v136 offset:4544
	s_waitcnt lgkmcnt(2)
	v_sub_f32_e32 v10, v10, v192
	v_mul_f32_e32 v10, v10, v193
	v_fma_f32 v10, v176, v10, v180
	v_sub_f32_e32 v11, v11, v192
	v_mul_f32_e32 v11, v11, v193
	v_fma_f32 v11, v177, v11, v181
	v_sub_f32_e32 v12, v12, v192
	v_mul_f32_e32 v12, v12, v193
	v_fma_f32 v12, v178, v12, v182
	v_sub_f32_e32 v13, v13, v192
	v_mul_f32_e32 v13, v13, v193
	v_fma_f32 v13, v179, v13, v183
	v_cvt_pk_bf16_f32 v152, v10, v11
	v_cvt_pk_bf16_f32 v153, v12, v13
	s_waitcnt lgkmcnt(0)
	v_sub_f32_e32 v6, v6, v192
	v_mul_f32_e32 v6, v6, v193
	v_fma_f32 v6, v184, v6, v188
	v_sub_f32_e32 v7, v7, v192
	v_mul_f32_e32 v7, v7, v193
	v_fma_f32 v7, v185, v7, v189
	v_sub_f32_e32 v8, v8, v192
	v_mul_f32_e32 v8, v8, v193
	v_fma_f32 v8, v186, v8, v190
	v_sub_f32_e32 v9, v9, v192
	v_mul_f32_e32 v9, v9, v193
	v_fma_f32 v9, v187, v9, v191
	v_cvt_pk_bf16_f32 v154, v6, v7
	v_cvt_pk_bf16_f32 v155, v8, v9
	s_nop 1
	v_permlane16_swap_b32 v152, v154
	v_permlane16_swap_b32 v153, v155
	global_store_dwordx4 v137, v[152:155], s[94:95] sc1
	s_waitcnt vmcnt(8) lgkmcnt(0)
	s_barrier
; DI float bf2f(unsigned b) { return __uint_as_float(b << 16); }
; DI void unit_O(const Params& p, char* lds, int l, int tile, int glu_tiles, int tile_b) {
;     ...
;         float s2[2], ss2[2];
; #pragma unroll
;         for (int mh = 0; mh < 2; ++mh) {
;             const int mt = half * 2 + mh, rl = mh * 16 + l15;
;             float s = 0.f, ss = 0.f;
; #pragma unroll
;             for (int nt = 0; nt < 8; ++nt) {
;                 f32x4 xr;
;                 if (l == 0) {
;                     const int chunk = wid * 32 + nt * 4 + quad;
;                     xr = *(const f32x4*)(XR + rl * 4096 + ((chunk ^ l15) << 4));
;                 } else {
;                     const u32x2 hb = *(const u32x2*)(XR + ((wid * 4 + (nt >> 1)) * 32 + rl) * 64 + (nt & 1) * 32 + quad * 8);
;                     xr = (f32x4){bf2f(hb[0] & 0xffffu), bf2f(hb[0] >> 16), bf2f(hb[1] & 0xffffu), bf2f(hb[1] >> 16)};
;                 }
; #pragma unroll
;                 for (int i = 0; i < 4; ++i) { const float v = acc[mt][nt][i] + DN_ALPHA * xr[i]; acc[mt][nt][i] = v; s += v; ss += v * v; }
;             }
;             s2[mh] = s; ss2[mh] = ss;
;         }
; #pragma unroll
;         for (int mh = 0; mh < 2; ++mh) { s2[mh] += __shfl_xor(s2[mh], 16); ss2[mh] += __shfl_xor(ss2[mh], 16); }
; #pragma unroll
;         for (int mh = 0; mh < 2; ++mh) { s2[mh] += __shfl_xor(s2[mh], 32); ss2[mh] += __shfl_xor(ss2[mh], 32); }
;         if (quad == 0) {
; #pragma unroll
;             for (int mh = 0; mh < 2; ++mh) *(f32x2*)&red[((mh * 16 + l15) * 8 + wid) * 2] = (f32x2){s2[mh], ss2[mh]};
;         }
;         __syncthreads();
	ds_read_b128 v[144:147], v204
	ds_read_b128 v[148:151], v205
	ds_read_b128 v[152:155], v206
	ds_read_b128 v[156:159], v207
	ds_read_b128 v[160:163], v204 offset:256
	ds_read_b128 v[164:167], v205 offset:256
	ds_read_b128 v[168:171], v206 offset:256
	ds_read_b128 v[172:175], v207 offset:256
	s_waitcnt lgkmcnt(7)
	v_fmac_f32_e32 v62, s58, v144
	v_fmac_f32_e32 v63, s58, v145
	v_fmac_f32_e32 v64, s58, v146
	v_fmac_f32_e32 v65, s58, v147
	v_mov_b32_e32 v196, v62
	v_mul_f32_e32 v197, v62, v62
	v_mov_b32_e32 v130, v63
	v_mul_f32_e32 v142, v63, v63
	v_add_f32_e32 v196, v196, v64
	v_fmac_f32_e32 v197, v64, v64
	v_add_f32_e32 v130, v130, v65
	v_fmac_f32_e32 v142, v65, v65
	s_waitcnt lgkmcnt(6)
	v_fmac_f32_e32 v58, s58, v148
	v_fmac_f32_e32 v59, s58, v149
	v_fmac_f32_e32 v60, s58, v150
	v_fmac_f32_e32 v61, s58, v151
	v_add_f32_e32 v196, v196, v58
	v_fmac_f32_e32 v197, v58, v58
	v_add_f32_e32 v130, v130, v59
	v_fmac_f32_e32 v142, v59, v59
	v_add_f32_e32 v196, v196, v60
	v_fmac_f32_e32 v197, v60, v60
	v_add_f32_e32 v130, v130, v61
	v_fmac_f32_e32 v142, v61, v61
	s_waitcnt lgkmcnt(5)
	v_fmac_f32_e32 v54, s58, v152
	v_fmac_f32_e32 v55, s58, v153
	v_fmac_f32_e32 v56, s58, v154
	v_fmac_f32_e32 v57, s58, v155
	v_add_f32_e32 v196, v196, v54
	v_fmac_f32_e32 v197, v54, v54
	v_add_f32_e32 v130, v130, v55
	v_fmac_f32_e32 v142, v55, v55
	v_add_f32_e32 v196, v196, v56
	v_fmac_f32_e32 v197, v56, v56
	v_add_f32_e32 v130, v130, v57
	v_fmac_f32_e32 v142, v57, v57
	s_waitcnt lgkmcnt(4)
	v_fmac_f32_e32 v50, s58, v156
	v_fmac_f32_e32 v51, s58, v157
	v_fmac_f32_e32 v52, s58, v158
	v_fmac_f32_e32 v53, s58, v159
	v_add_f32_e32 v196, v196, v50
	v_fmac_f32_e32 v197, v50, v50
	v_add_f32_e32 v130, v130, v51
	v_fmac_f32_e32 v142, v51, v51
	v_add_f32_e32 v196, v196, v52
	v_fmac_f32_e32 v197, v52, v52
	v_add_f32_e32 v130, v130, v53
	v_fmac_f32_e32 v142, v53, v53
	s_waitcnt lgkmcnt(3)
	v_fmac_f32_e32 v46, s58, v160
	v_fmac_f32_e32 v47, s58, v161
	v_fmac_f32_e32 v48, s58, v162
	v_fmac_f32_e32 v49, s58, v163
	v_add_f32_e32 v196, v196, v46
	v_fmac_f32_e32 v197, v46, v46
	v_add_f32_e32 v130, v130, v47
	v_fmac_f32_e32 v142, v47, v47
	v_add_f32_e32 v196, v196, v48
	v_fmac_f32_e32 v197, v48, v48
	v_add_f32_e32 v130, v130, v49
	v_fmac_f32_e32 v142, v49, v49
	s_waitcnt lgkmcnt(2)
	v_fmac_f32_e32 v42, s58, v164
	v_fmac_f32_e32 v43, s58, v165
	v_fmac_f32_e32 v44, s58, v166
	v_fmac_f32_e32 v45, s58, v167
	v_add_f32_e32 v196, v196, v42
	v_fmac_f32_e32 v197, v42, v42
	v_add_f32_e32 v130, v130, v43
	v_fmac_f32_e32 v142, v43, v43
	v_add_f32_e32 v196, v196, v44
	v_fmac_f32_e32 v197, v44, v44
	v_add_f32_e32 v130, v130, v45
	v_fmac_f32_e32 v142, v45, v45
	s_waitcnt lgkmcnt(1)
	v_fmac_f32_e32 v38, s58, v168
	v_fmac_f32_e32 v39, s58, v169
	v_fmac_f32_e32 v40, s58, v170
	v_fmac_f32_e32 v41, s58, v171
	v_add_f32_e32 v196, v196, v38
	v_fmac_f32_e32 v197, v38, v38
	v_add_f32_e32 v130, v130, v39
	v_fmac_f32_e32 v142, v39, v39
	v_add_f32_e32 v196, v196, v40
	v_fmac_f32_e32 v197, v40, v40
	v_add_f32_e32 v130, v130, v41
	v_fmac_f32_e32 v142, v41, v41
	s_waitcnt lgkmcnt(0)
	v_fmac_f32_e32 v2, s58, v172
	v_fmac_f32_e32 v3, s58, v173
	v_fmac_f32_e32 v4, s58, v174
	v_fmac_f32_e32 v5, s58, v175
	v_add_f32_e32 v196, v196, v2
	v_fmac_f32_e32 v197, v2, v2
	v_add_f32_e32 v130, v130, v3
	v_fmac_f32_e32 v142, v3, v3
	v_add_f32_e32 v196, v196, v4
	v_fmac_f32_e32 v197, v4, v4
	v_add_f32_e32 v130, v130, v5
	v_fmac_f32_e32 v142, v5, v5
	v_add_f32_e32 v196, v196, v130
	v_add_f32_e32 v197, v197, v142
	v_mov_b32_e32 v198, v196
	v_mov_b32_e32 v199, v197
	s_nop 1
	v_permlane16_swap_b32 v198, v196
	v_permlane16_swap_b32 v199, v197
	v_add_f32_e32 v196, v196, v198
	v_add_f32_e32 v197, v197, v199
	v_mov_b32_e32 v198, v196
	v_mov_b32_e32 v199, v197
	s_nop 1
	v_permlane32_swap_b32 v198, v196
	v_permlane32_swap_b32 v199, v197
	v_add_f32_e32 v196, v196, v198
	v_add_f32_e32 v197, v197, v199
	s_mov_b64 exec, 0xffff
	ds_write_b64 v134, v[196:197]
	s_mov_b64 exec, -1
	s_waitcnt lgkmcnt(0)
	s_barrier
; DI unsigned pk2(float lo, float hi) { const f32x2 v = {lo, hi}; const bf16x2_t b = __builtin_convertvector(v, bf16x2_t); return __builtin_bit_cast(unsigned, b); }
; DI size_t xb_off(int tok, int col) { return ((size_t)(((tok >> 7) * 32 + (col >> 5)) * 128 + (tok & 127))) * 32 + (col & 31); }
; DI void unit_O(const Params& p, char* lds, int l, int tile, int glu_tiles, int tile_b) {
;     ...
; #pragma unroll
;         for (int mh = 0; mh < 2; ++mh) {
;             const int mt = half * 2 + mh, rl = mh * 16 + l15, row = mt * 16 + l15;
;             float s = 0.f, ss = 0.f;
; #pragma unroll
;             for (int w = 0; w < 4; ++w) { const f32x4 v = *(const f32x4*)&red[rl * 16 + 4 * w]; s += v[0] + v[2]; ss += v[1] + v[3]; }
;             const float mu = s * (1.f / 1024.f);
;             const float var = ss * (1.f / 1024.f) - mu * mu;
;             const float rs = rsqrtf(var + LN_EPS);
;             float* orow = xo + (r0 + row) * 1024 + wid * 128 + quad * 4;
;             bf16_t* brow = xbo + xb_off((int)r0 + row, wid * 128) + quad * 4;
;             const float* gp = GB + wid * 128 + quad * 4;
; #pragma unroll
;             for (int nt = 0; nt < 8; ++nt) {
;                 const f32x4 g = *(const f32x4*)(gp + nt * 16), bb = *(const f32x4*)(gp + 1024 + nt * 16);
;                 f32x4 o;
; #pragma unroll
;                 for (int i = 0; i < 4; ++i) o[i] = (acc[mt][nt][i] - mu) * rs * g[i] + bb[i];
;                 if (l == 0) *(u32x2*)(brow + (nt >> 1) * 4096 + (nt & 1) * 16) = (u32x2){pk2(o[0], o[1]), pk2(o[2], o[3])};
;                 else *(f32x4*)(orow + nt * 16) = o;
;             }
	ds_read_b128 v[160:163], v135 offset:0
	ds_read_b128 v[164:167], v135 offset:16
	ds_read_b128 v[168:171], v135 offset:32
	ds_read_b128 v[172:175], v135 offset:48
	s_waitcnt lgkmcnt(0)
	v_add_f32_e32 v160, v160, v162
	v_add_f32_e32 v161, v161, v163
	v_add_f32_e32 v164, v164, v166
	v_add_f32_e32 v165, v165, v167
	v_add_f32_e32 v168, v168, v170
	v_add_f32_e32 v169, v169, v171
	v_add_f32_e32 v172, v172, v174
	v_add_f32_e32 v173, v173, v175
	v_add_f32_e32 v160, v160, v164
	v_add_f32_e32 v161, v161, v165
	v_add_f32_e32 v168, v168, v172
	v_add_f32_e32 v169, v169, v173
	v_add_f32_e32 v160, v160, v168
	v_add_f32_e32 v161, v161, v169
	v_mul_f32_e32 v192, 0x3a800000, v160
	v_mul_f32_e32 v193, 0x3a800000, v161
	v_fma_f32 v193, -v192, v192, v193
	v_add_f32_e32 v193, 0x3727c5ac, v193
	v_rsq_f32_e32 v193, v193
	s_nop 0
	s_add_u32 s94, s78, 0xc00
	s_addc_u32 s95, s79, 0
	ds_read_b128 v[176:179], v136
	ds_read_b128 v[180:183], v136 offset:4096
	ds_read_b128 v[184:187], v136 offset:64
	ds_read_b128 v[188:191], v136 offset:4160
	s_waitcnt lgkmcnt(2)
	v_sub_f32_e32 v62, v62, v192
	v_mul_f32_e32 v62, v62, v193
	v_fma_f32 v62, v176, v62, v180
	v_sub_f32_e32 v63, v63, v192
	v_mul_f32_e32 v63, v63, v193
	v_fma_f32 v63, v177, v63, v181
	v_sub_f32_e32 v64, v64, v192
	v_mul_f32_e32 v64, v64, v193
	v_fma_f32 v64, v178, v64, v182
	v_sub_f32_e32 v65, v65, v192
	v_mul_f32_e32 v65, v65, v193
	v_fma_f32 v65, v179, v65, v183
	v_cvt_pk_bf16_f32 v144, v62, v63
	v_cvt_pk_bf16_f32 v145, v64, v65
	ds_read_b128 v[176:179], v136 offset:128
	ds_read_b128 v[180:183], v136 offset:4224
	s_waitcnt lgkmcnt(2)
	v_sub_f32_e32 v58, v58, v192
	v_mul_f32_e32 v58, v58, v193
	v_fma_f32 v58, v184, v58, v188
	v_sub_f32_e32 v59, v59, v192
	v_mul_f32_e32 v59, v59, v193
	v_fma_f32 v59, v185, v59, v189
	v_sub_f32_e32 v60, v60, v192
	v_mul_f32_e32 v60, v60, v193
	v_fma_f32 v60, v186, v60, v190
	v_sub_f32_e32 v61, v61, v192
	v_mul_f32_e32 v61, v61, v193
	v_fma_f32 v61, v187, v61, v191
	v_cvt_pk_bf16_f32 v146, v58, v59
	v_cvt_pk_bf16_f32 v147, v60, v61
	s_nop 1
	v_permlane16_swap_b32 v144, v146
	v_permlane16_swap_b32 v145, v147
	global_store_dwordx4 v137, v[144:147], s[94:95] sc1
	s_add_u32 s94, s94, 0x2000
	s_addc_u32 s95, s95, 0
	ds_read_b128 v[184:187], v136 offset:192
	ds_read_b128 v[188:191], v136 offset:4288
	s_waitcnt lgkmcnt(2)
	v_sub_f32_e32 v54, v54, v192
	v_mul_f32_e32 v54, v54, v193
	v_fma_f32 v54, v176, v54, v180
	v_sub_f32_e32 v55, v55, v192
	v_mul_f32_e32 v55, v55, v193
	v_fma_f32 v55, v177, v55, v181
	v_sub_f32_e32 v56, v56, v192
	v_mul_f32_e32 v56, v56, v193
	v_fma_f32 v56, v178, v56, v182
	v_sub_f32_e32 v57, v57, v192
	v_mul_f32_e32 v57, v57, v193
	v_fma_f32 v57, v179, v57, v183
	v_cvt_pk_bf16_f32 v152, v54, v55
	v_cvt_pk_bf16_f32 v153, v56, v57
	ds_read_b128 v[176:179], v136 offset:256
	ds_read_b128 v[180:183], v136 offset:4352
	s_waitcnt lgkmcnt(2)
	v_sub_f32_e32 v50, v50, v192
	v_mul_f32_e32 v50, v50, v193
	v_fma_f32 v50, v184, v50, v188
	v_sub_f32_e32 v51, v51, v192
	v_mul_f32_e32 v51, v51, v193
	v_fma_f32 v51, v185, v51, v189
	v_sub_f32_e32 v52, v52, v192
	v_mul_f32_e32 v52, v52, v193
	v_fma_f32 v52, v186, v52, v190
	v_sub_f32_e32 v53, v53, v192
	v_mul_f32_e32 v53, v53, v193
	v_fma_f32 v53, v187, v53, v191
	v_cvt_pk_bf16_f32 v154, v50, v51
	v_cvt_pk_bf16_f32 v155, v52, v53
	s_nop 1
	v_permlane16_swap_b32 v152, v154
	v_permlane16_swap_b32 v153, v155
	global_store_dwordx4 v137, v[152:155], s[94:95] sc1
	s_add_u32 s94, s94, 0x2000
	s_addc_u32 s95, s95, 0
	ds_read_b128 v[184:187], v136 offset:320
	ds_read_b128 v[188:191], v136 offset:4416
	s_waitcnt lgkmcnt(2)
	v_sub_f32_e32 v46, v46, v192
	v_mul_f32_e32 v46, v46, v193
	v_fma_f32 v46, v176, v46, v180
	v_sub_f32_e32 v47, v47, v192
	v_mul_f32_e32 v47, v47, v193
	v_fma_f32 v47, v177, v47, v181
	v_sub_f32_e32 v48, v48, v192
	v_mul_f32_e32 v48, v48, v193
	v_fma_f32 v48, v178, v48, v182
	v_sub_f32_e32 v49, v49, v192
	v_mul_f32_e32 v49, v49, v193
	v_fma_f32 v49, v179, v49, v183
	v_cvt_pk_bf16_f32 v144, v46, v47
	v_cvt_pk_bf16_f32 v145, v48, v49
	ds_read_b128 v[176:179], v136 offset:384
	ds_read_b128 v[180:183], v136 offset:4480
	s_waitcnt lgkmcnt(2)
	v_sub_f32_e32 v42, v42, v192
	v_mul_f32_e32 v42, v42, v193
	v_fma_f32 v42, v184, v42, v188
	v_sub_f32_e32 v43, v43, v192
	v_mul_f32_e32 v43, v43, v193
	v_fma_f32 v43, v185, v43, v189
	v_sub_f32_e32 v44, v44, v192
	v_mul_f32_e32 v44, v44, v193
	v_fma_f32 v44, v186, v44, v190
	v_sub_f32_e32 v45, v45, v192
	v_mul_f32_e32 v45, v45, v193
	v_fma_f32 v45, v187, v45, v191
	v_cvt_pk_bf16_f32 v146, v42, v43
	v_cvt_pk_bf16_f32 v147, v44, v45
	s_nop 1
	v_permlane16_swap_b32 v144, v146
	v_permlane16_swap_b32 v145, v147
	global_store_dwordx4 v137, v[144:147], s[94:95] sc1
	s_add_u32 s94, s94, 0x2000
	s_addc_u32 s95, s95, 0
	ds_read_b128 v[184:187], v136 offset:448
	ds_read_b128 v[188:191], v136 offset:4544
	s_waitcnt lgkmcnt(2)
	v_sub_f32_e32 v38, v38, v192
	v_mul_f32_e32 v38, v38, v193
	v_fma_f32 v38, v176, v38, v180
	v_sub_f32_e32 v39, v39, v192
	v_mul_f32_e32 v39, v39, v193
	v_fma_f32 v39, v177, v39, v181
	v_sub_f32_e32 v40, v40, v192
	v_mul_f32_e32 v40, v40, v193
	v_fma_f32 v40, v178, v40, v182
	v_sub_f32_e32 v41, v41, v192
	v_mul_f32_e32 v41, v41, v193
	v_fma_f32 v41, v179, v41, v183
	v_cvt_pk_bf16_f32 v152, v38, v39
	v_cvt_pk_bf16_f32 v153, v40, v41
	s_waitcnt lgkmcnt(0)
	v_sub_f32_e32 v2, v2, v192
	v_mul_f32_e32 v2, v2, v193
	v_fma_f32 v2, v184, v2, v188
	v_sub_f32_e32 v3, v3, v192
	v_mul_f32_e32 v3, v3, v193
	v_fma_f32 v3, v185, v3, v189
	v_sub_f32_e32 v4, v4, v192
	v_mul_f32_e32 v4, v4, v193
	v_fma_f32 v4, v186, v4, v190
	v_sub_f32_e32 v5, v5, v192
	v_mul_f32_e32 v5, v5, v193
	v_fma_f32 v5, v187, v5, v191
	v_cvt_pk_bf16_f32 v154, v2, v3
	v_cvt_pk_bf16_f32 v155, v4, v5
	s_nop 1
	v_permlane16_swap_b32 v152, v154
	v_permlane16_swap_b32 v153, v155
	global_store_dwordx4 v137, v[152:155], s[94:95] sc1
	s_branch .Le1_done
